# retention scan: output convert+store block moved from the step tail into the state-update MFMA phase
# speedup vs baseline: 1.0042x; 1.0042x over previous
; #define LAS __attribute__((address_space(3)))
; __device__ __forceinline__ unsigned cvtpk(float lo, float hi) { unsigned r; asm volatile("v_cvt_pk_bf16_f32 %0, %1, %2" : "=v"(r) : "v"(lo), "v"(hi)); return r; }
; #define MF16(a, b, c) __builtin_amdgcn_mfma_f32_16x16x32_bf16((a), (b), (c), 0, 0, 0)
; __device__ __forceinline__ void ret_item(LAS unsigned char* lds, const bf16_t* proj, bf16_t* OD, int b, int h, int dir, int vs, float lg2) {
;     ...
;         RBAR();
;         {   f32x4 sa0 = (f32x4){0.f, 0.f, 0.f, 0.f}, sa1 = sa0;
;             s16x4 fq[2][2]; bf16x8 fk0[2], fk1[2];
;     ...
;             LDS_S(0, 0);
; #pragma unroll
;             for (int s = 0; s < 8; ++s) { if (s < 7) LDS_S((s + 1) & 1, s + 1); SCHED();
;                 const bf16x8 bq = cat(fq[s & 1][0], fq[s & 1][1]);
;                 __builtin_amdgcn_s_setprio(1); sa0 = MF16(fk0[s & 1], bq, sa0); sa1 = MF16(fk1[s & 1], bq, sa1); __builtin_amdgcn_s_setprio(0); SCHED(); }
;     ...
; #pragma unroll
;             for (int tt = 0; tt < 2; ++tt) { const f32x4 sv = tt ? sa1 : sa0; const int dt = dir ? (sjt0 + tt - sit) : (sit - sjt0 - tt);
;                 const float cs = dt <= 0 ? 1.f : dt == 1 ? c16 : dt == 2 ? c32 : c48; float w[4];
; #pragma unroll
;                 for (int r = 0; r < 4; ++r) { const bool on = dt > 0 || (dt == 0 && (dir ? (4 * g + r > l15) : (l15 >= 4 * g + r))); w[r] = on ? sv[r] * d4[r] * cs : 0.f; }
;                 u32x2 pkd; pkd.x = cvtpk(w[0], w[1]); pkd.y = cvtpk(w[2], w[3]);
;                 *(LAS u32x2*)(lds + SP + (16 * sit + l15) * RSS + (16 * (sjt0 + tt) + 4 * g) * 2) = pkd; }
;         }
;         RBAR();
;         f32x4 acc[4];
; #pragma unroll
;         for (int it = 0; it < 4; ++it) acc[it] = (f32x4){0.f, 0.f, 0.f, 0.f};
;         {   bf16x8 ca[2][4];
;     ...
;             LDS_C(0, 0);
; #pragma unroll
;             for (int s = 0; s < 8; ++s) { if (s < 7) LDS_C((s + 1) & 1, s + 1); SCHED();
;                 u32x4 bw; bw.x = cvtpk(st[2 * s][0], st[2 * s][1]); bw.y = cvtpk(st[2 * s][2], st[2 * s][3]); bw.z = cvtpk(st[2 * s + 1][0], st[2 * s + 1][1]); bw.w = cvtpk(st[2 * s + 1][2], st[2 * s + 1][3]);
;                 const bf16x8 bs = __builtin_bit_cast(bf16x8, bw);
;                 __builtin_amdgcn_s_setprio(1);
; #pragma unroll
;                 for (int it = 0; it < 4; ++it) acc[it] = MF16(bs, ca[s & 1][it], acc[it]);
;                 __builtin_amdgcn_s_setprio(0); SCHED(); }
.LBB0_140:
	s_add_i32 s20, s16, -1
	v_mov_b32_e32 v105, s20
	s_waitcnt lgkmcnt(0)
	s_barrier
	v_cndmask_b32_e64 v176, v104, v105, s[36:37]
	ds_read2_b64 v[104:107], v229 offset1:2
	ds_read_b128 v[108:111], v230 offset:36864
	ds_read_b128 v[112:115], v230 offset:46080
	ds_read2_b64 v[116:119], v229 offset0:8 offset1:10
	ds_read_b128 v[120:123], v230 offset:36928
	ds_read_b128 v[124:127], v230 offset:46144
	s_setprio 1
	s_waitcnt lgkmcnt(4)
	v_mfma_f32_16x16x32_bf16 v[108:111], v[108:111], v[104:107], 0
	s_waitcnt lgkmcnt(3)
	v_mfma_f32_16x16x32_bf16 v[104:107], v[112:115], v[104:107], 0
	s_setprio 0
	ds_read2_b64 v[112:115], v229 offset0:16 offset1:18
	ds_read_b128 v[128:131], v230 offset:36992
	ds_read_b128 v[132:135], v230 offset:46208
	s_setprio 1
	s_waitcnt lgkmcnt(4)
	v_mfma_f32_16x16x32_bf16 v[108:111], v[120:123], v[116:119], v[108:111]
	s_waitcnt lgkmcnt(3)
	v_mfma_f32_16x16x32_bf16 v[104:107], v[124:127], v[116:119], v[104:107]
	s_setprio 0
	ds_read2_b64 v[116:119], v229 offset0:24 offset1:26
	ds_read_b128 v[120:123], v230 offset:37056
	ds_read_b128 v[124:127], v230 offset:46272
	s_setprio 1
	s_waitcnt lgkmcnt(4)
	v_mfma_f32_16x16x32_bf16 v[108:111], v[128:131], v[112:115], v[108:111]
	s_waitcnt lgkmcnt(3)
	v_mfma_f32_16x16x32_bf16 v[104:107], v[132:135], v[112:115], v[104:107]
	s_setprio 0
	ds_read2_b64 v[112:115], v229 offset0:32 offset1:34
	ds_read_b128 v[128:131], v230 offset:37120
	ds_read_b128 v[132:135], v230 offset:46336
	s_setprio 1
	s_waitcnt lgkmcnt(4)
	v_mfma_f32_16x16x32_bf16 v[108:111], v[120:123], v[116:119], v[108:111]
	s_waitcnt lgkmcnt(3)
	v_mfma_f32_16x16x32_bf16 v[104:107], v[124:127], v[116:119], v[104:107]
	s_setprio 0
	ds_read2_b64 v[116:119], v229 offset0:40 offset1:42
	ds_read_b128 v[120:123], v230 offset:37184
	ds_read_b128 v[124:127], v230 offset:46400
	s_setprio 1
	s_waitcnt lgkmcnt(4)
	v_mfma_f32_16x16x32_bf16 v[108:111], v[128:131], v[112:115], v[108:111]
	s_waitcnt lgkmcnt(3)
	v_mfma_f32_16x16x32_bf16 v[104:107], v[132:135], v[112:115], v[104:107]
	s_setprio 0
	ds_read2_b64 v[112:115], v229 offset0:48 offset1:50
	ds_read_b128 v[128:131], v230 offset:37248
	ds_read_b128 v[132:135], v230 offset:46464
	s_setprio 1
	s_waitcnt lgkmcnt(4)
	v_mfma_f32_16x16x32_bf16 v[108:111], v[120:123], v[116:119], v[108:111]
	s_waitcnt lgkmcnt(3)
	v_mfma_f32_16x16x32_bf16 v[104:107], v[124:127], v[116:119], v[104:107]
	s_setprio 0
	ds_read2_b64 v[116:119], v229 offset0:56 offset1:58
	ds_read_b128 v[120:123], v230 offset:37312
	ds_read_b128 v[124:127], v230 offset:46528
	s_setprio 1
	s_waitcnt lgkmcnt(4)
	v_mfma_f32_16x16x32_bf16 v[108:111], v[128:131], v[112:115], v[108:111]
	s_waitcnt lgkmcnt(3)
	v_mfma_f32_16x16x32_bf16 v[104:107], v[132:135], v[112:115], v[104:107]
	s_setprio 0
	s_setprio 1
	s_waitcnt lgkmcnt(1)
	v_mfma_f32_16x16x32_bf16 v[108:111], v[120:123], v[116:119], v[108:111]
	s_waitcnt lgkmcnt(0)
	v_mfma_f32_16x16x32_bf16 v[104:107], v[124:127], v[116:119], v[104:107]
	s_setprio 0
	s_nop 4
	v_mul_f32_e32 v108, v199, v108
	v_mul_f32_e32 v109, v200, v109
	v_mul_f32_e32 v110, v201, v110
	v_mul_f32_e32 v108, v206, v108
	v_mul_f32_e32 v109, v206, v109
	v_mul_f32_e32 v110, v206, v110
	v_mul_f32_e32 v111, v202, v111
	v_mul_f32_e32 v104, v199, v104
	v_mul_f32_e32 v105, v200, v105
	v_mul_f32_e32 v106, v201, v106
	v_cndmask_b32_e64 v108, 0, v108, s[38:39]
	v_cndmask_b32_e64 v109, 0, v109, s[40:41]
	v_cndmask_b32_e64 v110, 0, v110, s[42:43]
	v_mul_f32_e32 v111, v206, v111
	v_mul_f32_e32 v104, v207, v104
	v_mul_f32_e32 v105, v207, v105
	v_mul_f32_e32 v106, v207, v106
	v_mul_f32_e32 v107, v202, v107
	v_cndmask_b32_e64 v111, 0, v111, s[44:45]
	v_cvt_pk_bf16_f32 v108, v108, v109
	v_cvt_pk_bf16_f32 v109, v110, v111
	v_add_u32_e32 v110, s17, v205
	v_cndmask_b32_e64 v104, 0, v104, s[46:47]
	v_cndmask_b32_e64 v105, 0, v105, s[48:49]
	v_cndmask_b32_e64 v106, 0, v106, s[50:51]
	v_mul_f32_e32 v107, v207, v107
	ds_write_b64 v110, v[108:109]
	v_cndmask_b32_e64 v107, 0, v107, s[52:53]
	v_cvt_pk_bf16_f32 v104, v104, v105
	v_cvt_pk_bf16_f32 v105, v106, v107
	v_add_u32_e32 v106, s18, v205
	ds_write_b64 v106, v[104:105]
	ds_read_b128 v[104:107], v231
	ds_read_b128 v[108:111], v231 offset:64
	ds_read_b128 v[112:115], v231 offset:9216
	ds_read_b128 v[116:119], v231 offset:9280
	ds_read_b128 v[120:123], v231 offset:18432
	ds_read_b128 v[124:127], v231 offset:18496
	ds_read_b128 v[128:131], v231 offset:27648
	ds_read_b128 v[132:135], v231 offset:27712
	v_cvt_pk_bf16_f32 v136, v40, v41
	v_cvt_pk_bf16_f32 v137, v42, v43
	v_cvt_pk_bf16_f32 v138, v52, v53
	v_cvt_pk_bf16_f32 v139, v54, v55
	s_setprio 1
	s_waitcnt lgkmcnt(7)
	v_mfma_f32_16x16x32_bf16 v[104:107], v[136:139], v[104:107], 0
	s_waitcnt lgkmcnt(5)
	v_mfma_f32_16x16x32_bf16 v[112:115], v[136:139], v[112:115], 0
	s_waitcnt lgkmcnt(3)
	v_mfma_f32_16x16x32_bf16 v[120:123], v[136:139], v[120:123], 0
	s_waitcnt lgkmcnt(1)
	v_mfma_f32_16x16x32_bf16 v[128:131], v[136:139], v[128:131], 0
	s_setprio 0
	ds_read_b128 v[136:139], v231 offset:128
	ds_read_b128 v[140:143], v231 offset:9344
	ds_read_b128 v[144:147], v231 offset:18560
	ds_read_b128 v[148:151], v231 offset:27776
	v_cvt_pk_bf16_f32 v152, v48, v49
	v_cvt_pk_bf16_f32 v153, v50, v51
	v_cvt_pk_bf16_f32 v154, v44, v45
	v_cvt_pk_bf16_f32 v155, v46, v47
	s_setprio 1
	v_mfma_f32_16x16x32_bf16 v[104:107], v[152:155], v[108:111], v[104:107]
	v_mfma_f32_16x16x32_bf16 v[108:111], v[152:155], v[116:119], v[112:115]
	v_mfma_f32_16x16x32_bf16 v[112:115], v[152:155], v[124:127], v[120:123]
	s_waitcnt lgkmcnt(4)
; __device__ __forceinline__ unsigned cvtpk(float lo, float hi) { unsigned r; asm volatile("v_cvt_pk_bf16_f32 %0, %1, %2" : "=v"(r) : "v"(lo), "v"(hi)); return r; }
; #define MF16(a, b, c) __builtin_amdgcn_mfma_f32_16x16x32_bf16((a), (b), (c), 0, 0, 0)
; __device__ __forceinline__ unsigned cvtpk(float lo, float hi) { unsigned r; asm volatile("v_cvt_pk_bf16_f32 %0, %1, %2" : "=v"(r) : "v"(lo), "v"(hi)); return r; }
; #define SCHED() __builtin_amdgcn_sched_barrier(0)
; #define LDS_C(buf, s) do { _Pragma("unroll") for (int it = 0; it < 4; ++it) ca[buf][it] = *(const LAS bf16x8*)(pCq + 16 * it * RSQ + 64 * (s)); } while (0)
; __device__ __forceinline__ void ret_item(LAS unsigned char* lds, const bf16_t* proj, bf16_t* OD, int b, int h, int dir, int vs, float lg2) {
;     ...
;         {   bf16x8 ca[2][4];
;     ...
;             LDS_C(0, 0);
; #pragma unroll
;             for (int s = 0; s < 8; ++s) { if (s < 7) LDS_C((s + 1) & 1, s + 1); SCHED();
;                 u32x4 bw; bw.x = cvtpk(st[2 * s][0], st[2 * s][1]); bw.y = cvtpk(st[2 * s][2], st[2 * s][3]); bw.z = cvtpk(st[2 * s + 1][0], st[2 * s + 1][1]); bw.w = cvtpk(st[2 * s + 1][2], st[2 * s + 1][3]);
;                 const bf16x8 bs = __builtin_bit_cast(bf16x8, bw);
;                 __builtin_amdgcn_s_setprio(1);
; #pragma unroll
;                 for (int it = 0; it < 4; ++it) acc[it] = MF16(bs, ca[s & 1][it], acc[it]);
;                 __builtin_amdgcn_s_setprio(0); SCHED(); }
;     ...
;         }
	v_mfma_f32_16x16x32_bf16 v[116:119], v[152:155], v[132:135], v[128:131]
	s_setprio 0
	ds_read_b128 v[120:123], v231 offset:192
	ds_read_b128 v[124:127], v231 offset:9408
	ds_read_b128 v[128:131], v231 offset:18624
	ds_read_b128 v[132:135], v231 offset:27840
	v_cvt_pk_bf16_f32 v152, v68, v69
	v_cvt_pk_bf16_f32 v153, v70, v71
	v_cvt_pk_bf16_f32 v154, v64, v65
	v_cvt_pk_bf16_f32 v155, v66, v67
	s_setprio 1
	s_waitcnt lgkmcnt(7)
	v_mfma_f32_16x16x32_bf16 v[104:107], v[152:155], v[136:139], v[104:107]
	s_waitcnt lgkmcnt(6)
	v_mfma_f32_16x16x32_bf16 v[108:111], v[152:155], v[140:143], v[108:111]
	s_waitcnt lgkmcnt(5)
	v_mfma_f32_16x16x32_bf16 v[112:115], v[152:155], v[144:147], v[112:115]
	s_waitcnt lgkmcnt(4)
	v_mfma_f32_16x16x32_bf16 v[116:119], v[152:155], v[148:151], v[116:119]
	s_setprio 0
	ds_read_b128 v[136:139], v231 offset:256
	ds_read_b128 v[140:143], v231 offset:9472
	ds_read_b128 v[144:147], v231 offset:18688
	ds_read_b128 v[148:151], v231 offset:27904
	v_cvt_pk_bf16_f32 v152, v60, v61
	v_cvt_pk_bf16_f32 v153, v62, v63
	v_cvt_pk_bf16_f32 v154, v56, v57
	v_cvt_pk_bf16_f32 v155, v58, v59
	s_setprio 1
	s_waitcnt lgkmcnt(7)
	v_mfma_f32_16x16x32_bf16 v[104:107], v[152:155], v[120:123], v[104:107]
	s_waitcnt lgkmcnt(6)
	v_mfma_f32_16x16x32_bf16 v[108:111], v[152:155], v[124:127], v[108:111]
	s_waitcnt lgkmcnt(5)
	v_mfma_f32_16x16x32_bf16 v[112:115], v[152:155], v[128:131], v[112:115]
	s_waitcnt lgkmcnt(4)
	v_mfma_f32_16x16x32_bf16 v[116:119], v[152:155], v[132:135], v[116:119]
	s_setprio 0
	ds_read_b128 v[120:123], v231 offset:320
	ds_read_b128 v[124:127], v231 offset:9536
	ds_read_b128 v[128:131], v231 offset:18752
	ds_read_b128 v[132:135], v231 offset:27968
	v_cvt_pk_bf16_f32 v152, v88, v89
	v_cvt_pk_bf16_f32 v153, v90, v91
	v_cvt_pk_bf16_f32 v154, v80, v81
	v_cvt_pk_bf16_f32 v155, v82, v83
	s_setprio 1
	s_waitcnt lgkmcnt(7)
	v_mfma_f32_16x16x32_bf16 v[104:107], v[152:155], v[136:139], v[104:107]
	s_waitcnt lgkmcnt(6)
	v_mfma_f32_16x16x32_bf16 v[108:111], v[152:155], v[140:143], v[108:111]
	s_waitcnt lgkmcnt(5)
	v_mfma_f32_16x16x32_bf16 v[112:115], v[152:155], v[144:147], v[112:115]
	s_waitcnt lgkmcnt(4)
	v_mfma_f32_16x16x32_bf16 v[116:119], v[152:155], v[148:151], v[116:119]
	s_setprio 0
	ds_read_b128 v[136:139], v231 offset:384
	ds_read_b128 v[140:143], v231 offset:9600
	ds_read_b128 v[144:147], v231 offset:18816
	ds_read_b128 v[148:151], v231 offset:28032
	v_cvt_pk_bf16_f32 v152, v76, v77
	v_cvt_pk_bf16_f32 v153, v78, v79
	v_cvt_pk_bf16_f32 v154, v72, v73
	v_cvt_pk_bf16_f32 v155, v74, v75
	s_setprio 1
	s_waitcnt lgkmcnt(7)
	v_mfma_f32_16x16x32_bf16 v[104:107], v[152:155], v[120:123], v[104:107]
	s_waitcnt lgkmcnt(6)
	v_mfma_f32_16x16x32_bf16 v[108:111], v[152:155], v[124:127], v[108:111]
	s_waitcnt lgkmcnt(5)
	v_mfma_f32_16x16x32_bf16 v[112:115], v[152:155], v[128:131], v[112:115]
	s_waitcnt lgkmcnt(4)
	v_mfma_f32_16x16x32_bf16 v[116:119], v[152:155], v[132:135], v[116:119]
	s_setprio 0
	ds_read_b128 v[120:123], v231 offset:448
	ds_read_b128 v[124:127], v231 offset:9664
	ds_read_b128 v[128:131], v231 offset:18880
	ds_read_b128 v[132:135], v231 offset:28096
	v_cvt_pk_bf16_f32 v152, v92, v93
	v_cvt_pk_bf16_f32 v153, v94, v95
	v_cvt_pk_bf16_f32 v154, v84, v85
	v_cvt_pk_bf16_f32 v155, v86, v87
	s_setprio 1
	s_waitcnt lgkmcnt(7)
	v_mfma_f32_16x16x32_bf16 v[104:107], v[152:155], v[136:139], v[104:107]
	s_waitcnt lgkmcnt(6)
	v_mfma_f32_16x16x32_bf16 v[108:111], v[152:155], v[140:143], v[108:111]
	s_waitcnt lgkmcnt(5)
	v_mfma_f32_16x16x32_bf16 v[112:115], v[152:155], v[144:147], v[112:115]
	s_waitcnt lgkmcnt(4)
	v_mfma_f32_16x16x32_bf16 v[116:119], v[152:155], v[148:151], v[116:119]
	s_setprio 0
	v_cvt_pk_bf16_f32 v136, v96, v97
	v_cvt_pk_bf16_f32 v137, v98, v99
	v_cvt_pk_bf16_f32 v138, v100, v101
	v_cvt_pk_bf16_f32 v139, v102, v103
	s_setprio 1
	s_waitcnt lgkmcnt(3)
	v_mfma_f32_16x16x32_bf16 v[104:107], v[136:139], v[120:123], v[104:107]
	s_waitcnt lgkmcnt(2)
	v_mfma_f32_16x16x32_bf16 v[108:111], v[136:139], v[124:127], v[108:111]
	s_waitcnt lgkmcnt(1)
	v_mfma_f32_16x16x32_bf16 v[112:115], v[136:139], v[128:131], v[112:115]
	s_waitcnt lgkmcnt(0)
	v_mfma_f32_16x16x32_bf16 v[116:119], v[136:139], v[132:135], v[116:119]
	s_setprio 0
	s_waitcnt lgkmcnt(0)
	s_barrier
; #define LAS __attribute__((address_space(3)))
; __device__ __forceinline__ unsigned cvtpk(float lo, float hi) { unsigned r; asm volatile("v_cvt_pk_bf16_f32 %0, %1, %2" : "=v"(r) : "v"(lo), "v"(hi)); return r; }
; __device__ __forceinline__ s16x4 trd(LAS unsigned char* p) { return __builtin_bit_cast(s16x4, __builtin_amdgcn_ds_read_tr16_b64_v4i16((LAS s16x4*)p)); }
; __device__ __forceinline__ bf16x8 cat(s16x4 a, s16x4 b) { return (bf16x8){a[0], a[1], a[2], a[3], b[0], b[1], b[2], b[3]}; }
; #define MF16(a, b, c) __builtin_amdgcn_mfma_f32_16x16x32_bf16((a), (b), (c), 0, 0, 0)
; #define SCHED() __builtin_amdgcn_sched_barrier(0)
; __device__ __forceinline__ void ret_item(LAS unsigned char* lds, const bf16_t* proj, bf16_t* OD, int b, int h, int dir, int vs, float lg2) {
;     ...
;         bf16x8 bv[2], ia[2][4];
; #pragma unroll
;         for (int s = 0; s < 2; ++s) { bv[s] = cat(trd(pVt + 32 * s * RSV), trd(pVt + (32 * s + 4) * RSV));
; #pragma unroll
;             for (int it = 0; it < 4; ++it) ia[s][it] = *(const LAS bf16x8*)(pIs + 16 * it * RSS + 64 * s); }
;         s16x4 ua[2][4][2];
;     ...
;         LDS_U(0, 0);
;         SCHED();
; #pragma unroll
;         for (int it = 0; it < 4; ++it) { const int ex = dir ? 3 - it : it; const float cq = qdl * (ex == 0 ? 1.f : ex == 1 ? c16 : ex == 2 ? c32 : c48); acc[it] = acc[it] * cq; }
; #pragma unroll
;         for (int s = 0; s < 2; ++s)
; #pragma unroll
;             for (int it = 0; it < 4; ++it) acc[it] = MF16(bv[s], ia[s][it], acc[it]);
;         SCHED();
; #pragma unroll
;         for (int i = 0; i < 16; ++i) st[i] = st[i] * cd;
;         bf16x8 bvd[2];
; #pragma unroll
;         for (int s = 0; s < 2; ++s) { const float ck = (dir ? s : 1 - s) ? c32 : 1.f; float e[8];
; #pragma unroll
;             for (int jj = 0; jj < 8; ++jj) e[jj] = bf2f((unsigned short)bv[s][jj]) * (kd8[jj] * ck);
;             u32x4 bw; bw.x = cvtpk(e[0], e[1]); bw.y = cvtpk(e[2], e[3]); bw.z = cvtpk(e[4], e[5]); bw.w = cvtpk(e[6], e[7]);
;             bvd[s] = __builtin_bit_cast(bf16x8, bw); }
; #pragma unroll
;         for (int u = 0; u < 8; ++u) { if (u < 7) LDS_U((u + 1) & 1, u + 1); SCHED();
;             __builtin_amdgcn_s_setprio(1);
; #pragma unroll
;             for (int k = 0; k < 4; ++k) st[4 * (u & 3) + k] = MF16(cat(ua[u & 1][k][0], ua[u & 1][k][1]), bvd[u >> 2], st[4 * (u & 3) + k]);
	ds_read_b64_tr_b16 v[140:141], v232
	ds_read_b64_tr_b16 v[142:143], v232 offset:1088
	ds_read_b64_tr_b16 v[136:137], v232 offset:8704
	ds_read_b64_tr_b16 v[138:139], v232 offset:9792
	ds_read_b128 v[144:147], v233
	ds_read_b128 v[148:151], v233 offset:64
	ds_read_b128 v[152:155], v233 offset:2304
	ds_read_b128 v[156:159], v233 offset:2368
	ds_read_b128 v[236:239], v233 offset:4608
	ds_read_b128 v[240:243], v233 offset:4672
	ds_read_b128 v[244:247], v233 offset:6912
	ds_read_b128 v[248:251], v233 offset:6976
	v_add_u32_e32 v235, v204, v203
	ds_read_b64_tr_b16 v[128:129], v235 offset:36864
	ds_read_b64_tr_b16 v[130:131], v235 offset:39168
	ds_read_b64_tr_b16 v[126:127], v235 offset:39232
	ds_read_b64_tr_b16 v[124:125], v235 offset:36928
	ds_read_b64_tr_b16 v[132:133], v234 offset:36896
	ds_read_b64_tr_b16 v[134:135], v234 offset:39200
	ds_read_b64_tr_b16 v[122:123], v234 offset:39264
	ds_read_b64_tr_b16 v[120:121], v234 offset:36960
	v_pk_mul_f32 v[106:107], v[180:181], v[106:107]
	v_pk_mul_f32 v[104:105], v[178:179], v[104:105]
	v_pk_mul_f32 v[114:115], v[188:189], v[114:115]
	v_pk_mul_f32 v[112:113], v[186:187], v[112:113]
	s_waitcnt lgkmcnt(14)
	v_mfma_f32_16x16x32_bf16 v[104:107], v[140:143], v[144:147], v[104:107]
	v_mul_f32_e64 v110, v184, v110
	v_mul_f32_e64 v111, v185, v111
	v_pk_mul_f32 v[108:109], v[182:183], v[108:109]
	s_waitcnt lgkmcnt(11)
	v_mfma_f32_16x16x32_bf16 v[144:147], v[140:143], v[236:239], v[112:115]
	s_nop 2
	v_mul_f32_e64 v114, v192, v118
	v_mul_f32_e64 v115, v193, v119
	v_pk_mul_f32 v[112:113], v[190:191], v[116:117]
	v_mfma_f32_16x16x32_bf16 v[108:111], v[140:143], v[152:155], v[108:111]
	s_waitcnt lgkmcnt(9)
	v_mfma_f32_16x16x32_bf16 v[152:155], v[140:143], v[244:247], v[112:115]
	v_mfma_f32_16x16x32_bf16 v[116:119], v[136:139], v[148:151], v[104:107]
	v_mfma_f32_16x16x32_bf16 v[112:115], v[136:139], v[156:159], v[108:111]
	v_mfma_f32_16x16x32_bf16 v[108:111], v[136:139], v[240:243], v[144:147]
	s_waitcnt lgkmcnt(8)
	v_mfma_f32_16x16x32_bf16 v[104:107], v[136:139], v[248:251], v[152:155]
	v_mov_b32_e32 v165, v164
	s_nop 1
	v_pk_mul_f32 v[154:155], v[164:165], v[46:47]
	v_pk_mul_f32 v[152:153], v[174:175], v[44:45]
	v_pk_mul_f32 v[46:47], v[164:165], v[70:71]
	v_pk_mul_f32 v[44:45], v[174:175], v[68:69]
	v_pk_mul_f32 v[158:159], v[164:165], v[58:59]
	v_pk_mul_f32 v[156:157], v[174:175], v[56:57]
	v_pk_mul_f32 v[70:71], v[164:165], v[82:83]
	v_pk_mul_f32 v[68:69], v[174:175], v[80:81]
	v_pk_mul_f32 v[82:83], v[164:165], v[78:79]
	v_pk_mul_f32 v[80:81], v[174:175], v[76:77]
	v_pk_mul_f32 v[58:59], v[164:165], v[94:95]
	v_pk_mul_f32 v[56:57], v[174:175], v[92:93]
	v_pk_mul_f32 v[78:79], v[164:165], v[86:87]
	v_pk_mul_f32 v[76:77], v[174:175], v[84:85]
	v_lshlrev_b32_e32 v84, 16, v140
	v_and_b32_e32 v85, 0xffff0000, v140
	v_lshlrev_b32_e32 v86, 16, v141
	v_and_b32_e32 v87, 0xffff0000, v141
	v_lshlrev_b32_e32 v92, 16, v142
	v_and_b32_e32 v93, 0xffff0000, v142
	v_lshlrev_b32_e32 v94, 16, v143
	v_and_b32_e32 v95, 0xffff0000, v143
	v_mul_f32_e32 v84, v208, v84
	v_mul_f32_e32 v85, v209, v85
	v_mul_f32_e32 v86, v210, v86
	v_mul_f32_e32 v87, v211, v87
	v_mul_f32_e32 v92, v212, v92
	v_mul_f32_e32 v93, v213, v93
	v_mul_f32_e32 v94, v214, v94
	v_mul_f32_e32 v95, v215, v95
	v_pk_mul_f32 v[146:147], v[164:165], v[50:51]
	v_pk_mul_f32 v[144:145], v[174:175], v[48:49]
	v_pk_mul_f32 v[50:51], v[164:165], v[90:91]
	v_pk_mul_f32 v[48:49], v[174:175], v[88:89]
	v_pk_mul_f32 v[90:91], v[164:165], v[74:75]
	v_pk_mul_f32 v[88:89], v[174:175], v[72:73]
	v_pk_mul_f32 v[74:75], v[164:165], v[98:99]
	v_pk_mul_f32 v[72:73], v[174:175], v[96:97]
	v_cvt_pk_bf16_f32 v84, v84, v85
	v_cvt_pk_bf16_f32 v85, v86, v87
	v_cvt_pk_bf16_f32 v86, v92, v93
	v_cvt_pk_bf16_f32 v87, v94, v95
	v_lshlrev_b32_e32 v92, 16, v136
	v_and_b32_e32 v93, 0xffff0000, v136
	v_lshlrev_b32_e32 v94, 16, v137
	v_and_b32_e32 v95, 0xffff0000, v137
	v_lshlrev_b32_e32 v96, 16, v138
	v_and_b32_e32 v97, 0xffff0000, v138
	v_lshlrev_b32_e32 v98, 16, v139
	v_and_b32_e32 v99, 0xffff0000, v139
	v_mul_f32_e32 v92, v216, v92
	v_mul_f32_e32 v93, v217, v93
	v_mul_f32_e32 v94, v218, v94
	v_mul_f32_e32 v95, v219, v95
	v_mul_f32_e32 v96, v220, v96
	v_mul_f32_e32 v97, v221, v97
	v_mul_f32_e32 v98, v222, v98
	v_mul_f32_e32 v99, v223, v99
	v_pk_mul_f32 v[150:151], v[164:165], v[62:63]
	v_pk_mul_f32 v[148:149], v[174:175], v[60:61]
	v_pk_mul_f32 v[62:63], v[164:165], v[102:103]
	v_pk_mul_f32 v[60:61], v[174:175], v[100:101]
	v_cvt_pk_bf16_f32 v100, v92, v93
	v_cvt_pk_bf16_f32 v101, v94, v95
	v_cvt_pk_bf16_f32 v102, v96, v97
	v_cvt_pk_bf16_f32 v103, v98, v99
	ds_read_b64_tr_b16 v[92:93], v235 offset:36992
	ds_read_b64_tr_b16 v[94:95], v235 offset:39296
	ds_read_b64_tr_b16 v[96:97], v234 offset:37024
	ds_read_b64_tr_b16 v[98:99], v234 offset:39328
	ds_read_b64_tr_b16 v[136:137], v235 offset:37056
	ds_read_b64_tr_b16 v[138:139], v235 offset:39360
	ds_read_b64_tr_b16 v[140:141], v234 offset:37088
	ds_read_b64_tr_b16 v[142:143], v234 offset:39392
	v_pk_mul_f32 v[42:43], v[164:165], v[42:43]
	v_pk_mul_f32 v[40:41], v[174:175], v[40:41]
	v_pk_mul_f32 v[54:55], v[164:165], v[54:55]
	v_pk_mul_f32 v[52:53], v[174:175], v[52:53]
	v_pk_mul_f32 v[66:67], v[164:165], v[66:67]
	v_pk_mul_f32 v[64:65], v[174:175], v[64:65]
	s_setprio 1
	s_waitcnt lgkmcnt(14)
	v_mfma_f32_16x16x32_bf16 v[40:43], v[128:131], v[84:87], v[40:43]
	s_waitcnt lgkmcnt(10)
	v_mfma_f32_16x16x32_bf16 v[52:55], v[132:135], v[84:87], v[52:55]
	v_mfma_f32_16x16x32_bf16 v[124:127], v[124:127], v[84:87], v[144:147]
	s_waitcnt lgkmcnt(8)
; __device__ __forceinline__ unsigned cvtpk(float lo, float hi) { unsigned r; asm volatile("v_cvt_pk_bf16_f32 %0, %1, %2" : "=v"(r) : "v"(lo), "v"(hi)); return r; }
; __device__ __forceinline__ bf16x8 cat(s16x4 a, s16x4 b) { return (bf16x8){a[0], a[1], a[2], a[3], b[0], b[1], b[2], b[3]}; }
; #define MF16(a, b, c) __builtin_amdgcn_mfma_f32_16x16x32_bf16((a), (b), (c), 0, 0, 0)
; __device__ __forceinline__ unsigned cvtpk(float lo, float hi) { unsigned r; asm volatile("v_cvt_pk_bf16_f32 %0, %1, %2" : "=v"(r) : "v"(lo), "v"(hi)); return r; }
; #define SCHED() __builtin_amdgcn_sched_barrier(0)
; #define LDS_U(buf, u) do { _Pragma("unroll") for (int k = 0; k < 4; ++k) { LAS unsigned char* pb = ((k & 1) ? pKo : pKe) + 32 * ((u) >> 2) * RSQ + 32 * (4 * ((u) & 3) + k); ua[buf][k][0] = trd(pb); ua[buf][k][1] = trd(pb + 4 * RSQ); } } while (0)
; __device__ __forceinline__ void ret_item(LAS unsigned char* lds, const bf16_t* proj, bf16_t* OD, int b, int h, int dir, int vs, float lg2) {
;     ...
;         for (int u = 0; u < 8; ++u) { if (u < 7) LDS_U((u + 1) & 1, u + 1); SCHED();
;             __builtin_amdgcn_s_setprio(1);
; #pragma unroll
;             for (int k = 0; k < 4; ++k) st[4 * (u & 3) + k] = MF16(cat(ua[u & 1][k][0], ua[u & 1][k][1]), bvd[u >> 2], st[4 * (u & 3) + k]);
;             __builtin_amdgcn_s_setprio(0); SCHED(); }
;     ...
; #pragma unroll
;         for (int it = 0; it < 4; ++it) { u32x2 w; w.x = cvtpk(acc[it][0], acc[it][1]); w.y = cvtpk(acc[it][2], acc[it][3]); *(u32x2*)(Og + (t0 + 16 * it + l15) * 4096) = w; }
	v_mfma_f32_16x16x32_bf16 v[120:123], v[120:123], v[84:87], v[152:155]
	s_setprio 0
	v_lshl_or_b32 v176, v176, 18, v224
	v_cvt_pk_bf16_f32 v116, v116, v117
	v_cvt_pk_bf16_f32 v117, v118, v119
	v_lshl_add_u64 v[118:119], v[176:177], 1, v[160:161]
	global_store_dwordx2 v[118:119], v[116:117], off
	v_cvt_pk_bf16_f32 v112, v112, v113
	v_cvt_pk_bf16_f32 v113, v114, v115
	v_ashrrev_i32_e32 v115, 31, v176
	v_mov_b32_e32 v114, v176
	v_lshl_add_u64 v[114:115], v[114:115], 1, v[160:161]
	s_mov_b32 s20, 0x20000
	v_add_co_u32_e32 v116, vcc, s20, v114
	s_mov_b32 s20, 0x40000
	s_nop 0
	v_addc_co_u32_e32 v117, vcc, 0, v115, vcc
	global_store_dwordx2 v[116:117], v[112:113], off
	v_cvt_pk_bf16_f32 v108, v108, v109
	v_cvt_pk_bf16_f32 v109, v110, v111
	v_add_co_u32_e32 v110, vcc, s20, v114
	s_add_i32 s19, s19, -1
	s_nop 0
	v_addc_co_u32_e32 v111, vcc, 0, v115, vcc
	global_store_dwordx2 v[110:111], v[108:109], off
	v_cvt_pk_bf16_f32 v104, v104, v105
	v_cvt_pk_bf16_f32 v105, v106, v107
	v_add_co_u32_e32 v106, vcc, s65, v114
	s_add_i32 s16, s16, 1
	s_nop 0
	v_addc_co_u32_e32 v107, vcc, 0, v115, vcc
	global_store_dwordx2 v[106:107], v[104:105], off
	ds_read_b64_tr_b16 v[128:129], v235 offset:37120
	ds_read_b64_tr_b16 v[130:131], v235 offset:39424
	ds_read_b64_tr_b16 v[134:135], v235 offset:39488
	ds_read_b64_tr_b16 v[132:133], v235 offset:37184
	ds_read_b64_tr_b16 v[144:145], v234 offset:37152
	ds_read_b64_tr_b16 v[146:147], v234 offset:39456
	ds_read_b64_tr_b16 v[154:155], v234 offset:39520
	ds_read_b64_tr_b16 v[152:153], v234 offset:37216
	s_setprio 1
	s_waitcnt lgkmcnt(14)
	v_mfma_f32_16x16x32_bf16 v[92:95], v[92:95], v[84:87], v[44:47]
	s_waitcnt lgkmcnt(12)
	v_mfma_f32_16x16x32_bf16 v[64:67], v[96:99], v[84:87], v[64:67]
	s_waitcnt lgkmcnt(10)
	v_mfma_f32_16x16x32_bf16 v[96:99], v[136:139], v[84:87], v[148:151]
	s_waitcnt lgkmcnt(8)
	v_mfma_f32_16x16x32_bf16 v[136:139], v[140:143], v[84:87], v[156:159]
	s_setprio 0
	ds_read_b64_tr_b16 v[44:45], v235 offset:37248
	ds_read_b64_tr_b16 v[46:47], v235 offset:39552
	ds_read_b64_tr_b16 v[142:143], v235 offset:39616
	ds_read_b64_tr_b16 v[140:141], v235 offset:37312
	ds_read_b64_tr_b16 v[148:149], v234 offset:37280
	ds_read_b64_tr_b16 v[150:151], v234 offset:39584
	ds_read_b64_tr_b16 v[158:159], v234 offset:39648
	ds_read_b64_tr_b16 v[156:157], v234 offset:37344
	s_setprio 1
	s_waitcnt lgkmcnt(14)
	v_mfma_f32_16x16x32_bf16 v[128:131], v[128:131], v[84:87], v[48:51]
	s_waitcnt lgkmcnt(10)
	v_mfma_f32_16x16x32_bf16 v[144:147], v[144:147], v[84:87], v[68:71]
	v_mfma_f32_16x16x32_bf16 v[132:135], v[132:135], v[84:87], v[80:83]
	s_waitcnt lgkmcnt(8)
	v_mfma_f32_16x16x32_bf16 v[152:155], v[152:155], v[84:87], v[88:91]
	s_setprio 0
	ds_read_b64_tr_b16 v[48:49], v235 offset:55296
	ds_read_b64_tr_b16 v[50:51], v235 offset:57600
	ds_read_b64_tr_b16 v[70:71], v235 offset:57664
	ds_read_b64_tr_b16 v[68:69], v235 offset:55360
	ds_read_b64_tr_b16 v[80:81], v234 offset:55328
	ds_read_b64_tr_b16 v[82:83], v234 offset:57632
	ds_read_b64_tr_b16 v[90:91], v234 offset:57696
	ds_read_b64_tr_b16 v[88:89], v234 offset:55392
	s_setprio 1
	s_waitcnt lgkmcnt(14)
	v_mfma_f32_16x16x32_bf16 v[236:239], v[44:47], v[84:87], v[56:59]
	s_waitcnt lgkmcnt(10)
	v_mfma_f32_16x16x32_bf16 v[148:151], v[148:151], v[84:87], v[76:79]
	v_mfma_f32_16x16x32_bf16 v[140:143], v[140:143], v[84:87], v[72:75]
	s_waitcnt lgkmcnt(8)
	v_mfma_f32_16x16x32_bf16 v[156:159], v[156:159], v[84:87], v[60:63]
	s_setprio 0
	ds_read_b64_tr_b16 v[56:57], v235 offset:55424
	ds_read_b64_tr_b16 v[58:59], v235 offset:57728
	ds_read_b64_tr_b16 v[62:63], v235 offset:57792
	ds_read_b64_tr_b16 v[60:61], v235 offset:55488
	ds_read_b64_tr_b16 v[72:73], v234 offset:55456
	ds_read_b64_tr_b16 v[74:75], v234 offset:57760
	ds_read_b64_tr_b16 v[78:79], v234 offset:57824
	ds_read_b64_tr_b16 v[76:77], v234 offset:55520
	s_setprio 1
	s_waitcnt lgkmcnt(14)
	v_mfma_f32_16x16x32_bf16 v[40:43], v[48:51], v[100:103], v[40:43]
	s_waitcnt lgkmcnt(10)
	v_mfma_f32_16x16x32_bf16 v[52:55], v[80:83], v[100:103], v[52:55]
	v_mfma_f32_16x16x32_bf16 v[48:51], v[68:71], v[100:103], v[124:127]
	s_waitcnt lgkmcnt(8)
	v_mfma_f32_16x16x32_bf16 v[44:47], v[88:91], v[100:103], v[120:123]
	s_setprio 0
	ds_read_b64_tr_b16 v[80:81], v235 offset:55552
	ds_read_b64_tr_b16 v[82:83], v235 offset:57856
	ds_read_b64_tr_b16 v[86:87], v235 offset:57920
	ds_read_b64_tr_b16 v[84:85], v235 offset:55616
	ds_read_b64_tr_b16 v[120:121], v234 offset:55584
	ds_read_b64_tr_b16 v[122:123], v234 offset:57888
	ds_read_b64_tr_b16 v[126:127], v234 offset:57952
	ds_read_b64_tr_b16 v[124:125], v234 offset:55648
	s_setprio 1
	s_waitcnt lgkmcnt(14)
	v_mfma_f32_16x16x32_bf16 v[68:71], v[56:59], v[100:103], v[92:95]
	s_waitcnt lgkmcnt(10)
	v_mfma_f32_16x16x32_bf16 v[64:67], v[72:75], v[100:103], v[64:67]
	v_mfma_f32_16x16x32_bf16 v[60:63], v[60:63], v[100:103], v[96:99]
	s_waitcnt lgkmcnt(8)
	v_mfma_f32_16x16x32_bf16 v[56:59], v[76:79], v[100:103], v[136:139]
	s_setprio 0
	ds_read_b64_tr_b16 v[92:93], v235 offset:55680
	ds_read_b64_tr_b16 v[94:95], v235 offset:57984
	ds_read_b64_tr_b16 v[98:99], v235 offset:58048
	ds_read_b64_tr_b16 v[96:97], v235 offset:55744
	ds_read_b64_tr_b16 v[136:137], v234 offset:55712
	ds_read_b64_tr_b16 v[138:139], v234 offset:58016
	ds_read_b64_tr_b16 v[242:243], v234 offset:58080
	ds_read_b64_tr_b16 v[240:241], v234 offset:55776
	s_setprio 1
	s_waitcnt lgkmcnt(14)
	v_mfma_f32_16x16x32_bf16 v[88:91], v[80:83], v[100:103], v[128:131]
	s_waitcnt lgkmcnt(10)
	v_mfma_f32_16x16x32_bf16 v[80:83], v[120:123], v[100:103], v[144:147]
	v_mfma_f32_16x16x32_bf16 v[76:79], v[84:87], v[100:103], v[132:135]
	s_waitcnt lgkmcnt(8)
	v_mfma_f32_16x16x32_bf16 v[72:75], v[124:127], v[100:103], v[152:155]
	s_setprio 0
	s_setprio 1
	s_waitcnt lgkmcnt(6)
	v_mfma_f32_16x16x32_bf16 v[92:95], v[92:95], v[100:103], v[236:239]
	s_waitcnt lgkmcnt(2)
	v_mfma_f32_16x16x32_bf16 v[84:87], v[136:139], v[100:103], v[148:151]
	v_mfma_f32_16x16x32_bf16 v[96:99], v[96:99], v[100:103], v[140:143]
	s_waitcnt lgkmcnt(0)
	v_mfma_f32_16x16x32_bf16 v[100:103], v[240:243], v[100:103], v[156:159]
	s_setprio 0
	s_waitcnt lgkmcnt(0)
	s_barrier
	s_cmp_lg_u32 s19, -2
	s_cbranch_scc0 .LBB0_138
